# v_m11 + scan claims per XCD (XCC_ID): the 4 row-group items sharing the same staging stream run on one XCD (16 items per XCD, own counters)
# baseline (speedup 1.0000x reference)
; DI void phase_attn_scan(const Params& p, int l, int half, char* smem, int rep) {
;   __shared__ int s_item;
;   const int n_scan = 128, n_lat = 3 * 512, n_ctx = (l == 0) ? 96 : 0;
;   const int n_gate = ((l == 0) ? 68 : 64) * 32;
;   const int n_conv = (l == 0 && half == 0) ? 128 : 0;
;   const int total = n_scan + n_conv + n_lat + n_ctx + n_gate;
;   unsigned* cnt = p.cnt + (l * 2 + half) + 8 * rep;
.LBB0_151:
	s_and_b64 vcc, exec, s[0:1]
	s_cbranch_vccz .LBB0_941
	v_readlane_b32 s0, v255, 20
	s_cmp_gt_i32 s0, 0
	s_mov_b64 s[0:1], -1
	s_cbranch_scc0 .LBB0_939
	v_readlane_b32 s0, v255, 20
	s_cmp_gt_i32 s0, 1
	s_mov_b64 s[0:1], -1
	s_cbranch_scc0 .LBB0_408
	v_readlane_b32 s0, v252, 2
	s_add_i32 s0, s0, 11
	s_cmp_gt_u32 s0, 26
	s_cselect_b64 s[12:13], -1, 0
	v_writelane_b32 v255, s12, 25
	v_readlane_b32 s1, v252, 3
	s_mov_b64 s[86:87], s[66:67]
	v_writelane_b32 v255, s13, 26
	s_mov_b64 s[84:85], s[64:65]
	v_readlane_b32 s12, v255, 17
	v_readlane_b32 s26, v255, 19
	s_or_b32 s1, s26, s12
	s_cmp_eq_u32 s1, 0
	s_mov_b64 s[82:83], s[62:63]
	s_mov_b64 s[80:81], s[60:61]
	s_mov_b64 s[78:79], s[58:59]
	s_mov_b64 s[76:77], s[56:57]
	s_mov_b64 s[74:75], s[54:55]
	s_mov_b64 s[72:73], s[52:53]
	s_mov_b32 s60, s12
	s_cselect_b32 s12, 0x80, 0
	s_cmp_lt_u32 s0, 27
	s_movk_i32 s0, 0x880
	s_cselect_b32 s21, s0, 0x800
	s_movk_i32 s0, 0xf0a0
	s_cselect_b32 s0, s0, 0xfffff180
	v_readlane_b32 s13, v255, 18
	v_writelane_b32 v255, s0, 30
	s_movk_i32 s0, 0xf920
	s_cselect_b32 s13, 0x60, 0
	s_cselect_b32 s0, s0, 0xfffff980
	v_writelane_b32 v255, s0, 27
	s_or_b32 s0, s21, s13
	s_add_i32 s0, s0, s12
	s_add_i32 s69, s0, 0x680
	s_lshl_b32 s0, s60, 1
	s_add_i32 s0, s0, s26
	s_ashr_i32 s1, s0, 31
	s_lshl_b64 s[0:1], s[0:1], 2
	s_add_u32 s0, s74, s0
	s_addc_u32 s1, s75, s1
	v_writelane_b32 v255, s0, 23
	s_lshl_b32 s28, s12, 8
	s_ashr_i32 s61, s60, 31
	v_writelane_b32 v255, s1, 24
	s_or_b32 s0, s13, 0x600
	v_writelane_b32 v255, s0, 32
	s_or_b32 s0, s0, s21
	v_writelane_b32 v255, s0, 28
	s_mul_i32 s0, s26, 0x4400
	v_writelane_b32 v255, s0, 34
	s_ashr_i32 s0, s0, 31
	s_mul_i32 s1, s60, 0x1f00
	v_writelane_b32 v255, s0, 35
	s_mul_hi_i32 s0, s60, 0x1f00
	s_add_u32 s1, s1, 0xf00
	v_writelane_b32 v255, s1, 36
	s_addc_u32 s0, s0, 0
	v_writelane_b32 v255, s0, 37
	s_lshl_b32 s0, s60, 12
	s_ashr_i32 s1, s0, 31
	s_lshl_b32 s12, s60, 6
	v_readlane_b32 s36, v252, 38
	s_ashr_i32 s13, s12, 31
	s_lshl_b64 s[0:1], s[0:1], 2
	v_readlane_b32 s38, v252, 40
	v_readlane_b32 s39, v252, 41
	s_add_u32 s0, s38, s0
	v_writelane_b32 v255, s0, 38
	s_addc_u32 s0, s39, s1
	v_writelane_b32 v255, s0, 39
	s_mov_b32 s0, s60
	v_writelane_b32 v255, s0, 17
	v_readlane_b32 s37, v252, 39
	s_mov_b32 s29, s27
	v_writelane_b32 v255, s1, 18
	s_lshl_b64 s[0:1], s[60:61], 2
	s_mov_b64 s[52:53], s[72:73]
	s_add_u32 s0, s52, s0
	s_addc_u32 s1, s53, s1
	v_writelane_b32 v255, s0, 40
	s_mov_b64 s[54:55], s[74:75]
	s_mov_b64 s[56:57], s[76:77]
	v_writelane_b32 v255, s1, 41
	s_lshl_b64 s[0:1], s[12:13], 2
	s_add_u32 s0, s36, s0
	s_addc_u32 s1, s37, s1
	v_writelane_b32 v255, s0, 42
	s_mov_b64 s[58:59], s[78:79]
	s_mov_b64 s[60:61], s[80:81]
	s_mov_b64 s[62:63], s[82:83]
	s_mov_b64 s[64:65], s[84:85]
	s_mov_b64 s[66:67], s[86:87]
	v_writelane_b32 v255, s1, 43
	v_readlane_b32 s40, v252, 42
	v_readlane_b32 s41, v252, 43
	v_readlane_b32 s42, v252, 44
	v_readlane_b32 s43, v252, 45
	v_readlane_b32 s44, v252, 46
	v_readlane_b32 s45, v252, 47
	v_readlane_b32 s46, v252, 48
	v_readlane_b32 s47, v252, 49
	v_readlane_b32 s48, v252, 50
	v_readlane_b32 s49, v252, 51
	v_readlane_b32 s50, v252, 52
	v_readlane_b32 s51, v252, 53
	s_getreg_b32 s0, hwreg(HW_REG_HW_ID, 16, 4)
	s_cmp_eq_u32 s0, 0
	s_cselect_b32 s1, 1, 0
	s_nop 0
	v_writelane_b32 v255, s1, 59
	s_getreg_b32 s0, hwreg(HW_REG_XCC_ID, 0, 4)
	s_and_b32 s0, s0, 7
	s_lshl_b32 s0, s0, 4
	s_nop 0
	v_writelane_b32 v255, s0, 58
	s_branch .LBB0_158

; DI void phase_attn_scan(const Params& p, int l, int half, char* smem, int rep) {
;     ...
;   for (;;) {
;     __syncthreads();
;     if (threadIdx.x == 0) s_item = (int)atomicAdd(cnt, 1u);
;     __syncthreads();
;     int it = s_item;
;     if (it >= total) break;
;     if (it < n_scan) { scan_item(p, it, smem); continue; }
.LBB0_158:
	s_barrier
	s_mov_b64 s[0:1], exec
	v_readlane_b32 s12, v252, 0
	v_readlane_b32 s13, v252, 1
	s_and_b64 s[12:13], s[0:1], s[12:13]
	s_mov_b64 exec, s[12:13]
	s_cbranch_execz .LBB0_162
	v_readlane_b32 s12, v255, 59
	s_cmp_eq_u32 s12, 0
	s_cbranch_scc1 .Lq_fetch
	v_writelane_b32 v255, 0, 59
	s_waitcnt vmcnt(3)
	v_readlane_b32 s36, v255, 23
	v_readlane_b32 s37, v255, 24
	v_readlane_b32 s21, v255, 58
	v_mov_b32_e32 v1, 1
	s_add_u32 s36, s36, s21
	s_addc_u32 s37, s37, 0
	s_nop 4
	global_atomic_add v1, v177, v1, s[36:37] offset:128 sc0
	s_waitcnt vmcnt(0)
	v_readfirstlane_b32 s12, v1
	s_cmpk_lt_u32 s12, 0x10
	s_cbranch_scc0 .Lq_fetch
	s_add_i32 s12, s12, s21
	v_mov_b32_e32 v0, s12
	ds_write_b32 v200, v0
	s_branch .LBB0_162

; DI int otid() { int t; asm volatile("v_mov_b32 %0, %1" : "=v"(t) : "v"((int)threadIdx.x)); return t; }
; DI void phase_attn_scan(const Params& p, int l, int half, char* smem, int rep) {
;     ...
;   for (;;) {
;     __syncthreads();
;     if (threadIdx.x == 0) s_item = (int)atomicAdd(cnt, 1u);
;     __syncthreads();
;     int it = s_item;
;     if (it >= total) break;
;     if (it < n_scan) { scan_item(p, it, smem); continue; }
;     it -= n_scan;
;     if (it >= n_lat + n_ctx + n_gate) { conv_layer(p, 1, (long)(it - n_lat - n_ctx - n_gate) * 256 + otid(), (long)n_conv * 256); continue; }
.LBB0_161:
	s_or_b64 exec, exec, s[12:13]
	s_waitcnt vmcnt(0)
	v_readfirstlane_b32 s12, v1
	s_nop 1
	v_add_u32_e32 v0, s12, v0
	v_add_u32_e32 v0, 0x80, v0
	v_cmp_le_i32_e32 vcc, s69, v0
	s_cbranch_vccz .Lq_store
	v_readlane_b32 s36, v255, 23
	v_readlane_b32 s37, v255, 24
	v_readlane_b32 s21, v255, 58
	v_mov_b32_e32 v1, 1
	s_add_u32 s36, s36, s21
	s_addc_u32 s37, s37, 0
	s_nop 4
	global_atomic_add v1, v177, v1, s[36:37] offset:128 sc0
	s_waitcnt vmcnt(0)
	v_cmp_gt_u32_e32 vcc, 0x10, v1
	v_add_u32_e32 v1, s21, v1
	s_nop 1
	v_cndmask_b32_e32 v0, v0, v1, vcc
